# convert_caches(layer 1): destination pointer load issued with the data loads (one round trip per iteration)
# speedup vs baseline: 1.0040x; 1.0040x over previous
; DI void convert_caches(const Params& p, int l) {
;     ...
;   for (long e = (long)blockIdx.x * 256 + tid; e < total; e += (long)gridDim.x * 256) {
;     const int row = (int)(e / 40), c = (int)(e - (long)row * 40);
;     const int b = row >> 11, pos = row & 2047;
;     const size_t drow = (size_t)16384 + (size_t)b * 2112 + pos;
;     const size_t srow = (size_t)(l * 32 + b) * 2048 + pos;
;     if (c < 16) *(bf16x8*)(p.KB + drow * 128 + c * 8) = cvt8(p.cache_k + srow * 128 + c * 8);
;     else if (c < 32) *(bf16x8*)(p.VB + drow * 128 + (c - 16) * 8) = cvt8(p.cache_v + srow * 128 + (c - 16) * 8);
;     else *(bf16x8*)(p.KIB + drow * 64 + (c - 32) * 8) = cvt8(p.cache_kidx + srow * 64 + (c - 32) * 8);
;   }
.LBB0_139:
	s_or_b64 exec, exec, s[8:9]
	v_mul_hi_i32_i24_e32 v13, 0x840, v12
	v_mul_i32_i24_e32 v12, 0x840, v12
	v_lshl_add_u64 v[12:13], v[12:13], 0, v[14:15]
	s_mov_b64 s[8:9], 0x4000
	v_lshl_add_u64 v[26:27], v[12:13], 0, s[8:9]
	global_load_dwordx4 v[12:15], v[18:19], off offset:16
	global_load_dwordx4 v[22:25], v[18:19], off
	global_load_dwordx2 v[28:29], v[20:21], off
	v_readlane_b32 s8, v254, 12
	v_readlane_b32 s9, v254, 13
	s_waitcnt vmcnt(0)
	v_cvt_pk_bf16_f32 v22, v22, v23
	v_cvt_pk_bf16_f32 v23, v24, v25
	v_cvt_pk_bf16_f32 v24, v12, v13
	v_lshl_add_u64 v[4:5], v[4:5], 0, s[8:9]
	v_readlane_b32 s8, v254, 45
	v_readlane_b32 s9, v254, 46
	v_cvt_pk_bf16_f32 v25, v14, v15
	v_lshlrev_b64 v[14:15], v16, v[26:27]
	v_lshl_add_u64 v[6:7], v[6:7], 0, s[8:9]
	v_readlane_b32 s8, v254, 34
	v_lshl_add_u64 v[12:13], v[28:29], 0, v[14:15]
	v_add_u32_e32 v8, s8, v8
	s_mov_b64 s[8:9], 0x27ffff
	v_cmp_lt_i64_e32 vcc, s[8:9], v[4:5]
	v_lshl_add_u64 v[10:11], v[10:11], 1, v[12:13]
	s_or_b64 s[6:7], vcc, s[6:7]
	global_store_dwordx4 v[10:11], v[22:25], off
	s_andn2_b64 exec, exec, s[6:7]
	s_cbranch_execz .LBB0_148
